# kind-1 GEMM bf16 epilogue: wave owns 64 adjacent columns (weight rows restaged) and each 16-row group is transposed through a private LDS buffer so stores are 8 rows x 128 B with adjacent lanes contig
# speedup vs baseline: 1.0241x; 1.0241x over previous
.LBB0_678:
	v_lshrrev_b32_e32 v112, 6, v146
	v_bfe_u32 v114, v148, 5, 2
	v_lshl_add_u32 v112, v112, 2, v114
	v_mul_u32_u24_e32 v112, 2304, v112
	v_add_u32_e32 v112, 135424, v112
	v_and_b32_e32 v114, 15, v189
	v_mul_u32_u24_e32 v114, 144, v114
	v_lshrrev_b32_e32 v115, 4, v189
	v_lshl_add_u32 v114, v115, 4, v114
	v_add_u32_e32 v190, v112, v114
	v_lshrrev_b32_e32 v114, 3, v189
	v_and_b32_e32 v115, 7, v189
	v_mul_u32_u24_e32 v191, 144, v114
	v_lshl_add_u32 v191, v115, 4, v191
	v_add_u32_e32 v191, v112, v191
	v_and_b32_e32 v112, 0xfffffff0, v146
	v_add_u32_e32 v112, v112, v114
	v_lshl_add_u32 v112, s53, 8, v112
	v_and_b32_e32 v114, 0x60, v148
	v_lshl_add_u32 v114, v114, 1, 0
	v_lshl_add_u32 v114, v115, 3, v114
	v_lshl_add_u32 v114, s52, 8, v114
	v_mad_u32_u24 v144, v112, s6, v114
	s_lshl_b32 s21, s6, 4
	v_lshlrev_b32_e32 v144, 1, v144
	s_andn2_b64 vcc, exec, s[4:5]
	v_add_u32_e32 v145, s21, v144
	s_cbranch_vccnz .Lg1e_norelu
	v_max_f32_e32 v0, 0, v0
	v_max_f32_e32 v1, 0, v1
	v_max_f32_e32 v2, 0, v2
	v_max_f32_e32 v3, 0, v3
	v_max_f32_e32 v4, 0, v4
	v_max_f32_e32 v5, 0, v5
	v_max_f32_e32 v6, 0, v6
	v_max_f32_e32 v7, 0, v7
	v_max_f32_e32 v8, 0, v8
	v_max_f32_e32 v9, 0, v9
	v_max_f32_e32 v10, 0, v10
	v_max_f32_e32 v11, 0, v11
	v_max_f32_e32 v12, 0, v12
	v_max_f32_e32 v13, 0, v13
	v_max_f32_e32 v14, 0, v14
	v_max_f32_e32 v15, 0, v15
	v_max_f32_e32 v16, 0, v16
	v_max_f32_e32 v17, 0, v17
	v_max_f32_e32 v18, 0, v18
	v_max_f32_e32 v19, 0, v19
	v_max_f32_e32 v20, 0, v20
	v_max_f32_e32 v21, 0, v21
	v_max_f32_e32 v22, 0, v22
	v_max_f32_e32 v23, 0, v23
	v_max_f32_e32 v24, 0, v24
	v_max_f32_e32 v25, 0, v25
	v_max_f32_e32 v26, 0, v26
	v_max_f32_e32 v27, 0, v27
	v_max_f32_e32 v28, 0, v28
	v_max_f32_e32 v29, 0, v29
	v_max_f32_e32 v30, 0, v30
	v_max_f32_e32 v31, 0, v31
	v_max_f32_e32 v32, 0, v32
	v_max_f32_e32 v33, 0, v33
	v_max_f32_e32 v34, 0, v34
	v_max_f32_e32 v35, 0, v35
	v_max_f32_e32 v36, 0, v36
	v_max_f32_e32 v37, 0, v37
	v_max_f32_e32 v38, 0, v38
	v_max_f32_e32 v39, 0, v39
	v_max_f32_e32 v40, 0, v40
	v_max_f32_e32 v41, 0, v41
	v_max_f32_e32 v42, 0, v42
	v_max_f32_e32 v43, 0, v43
	v_max_f32_e32 v44, 0, v44
	v_max_f32_e32 v45, 0, v45
	v_max_f32_e32 v46, 0, v46
	v_max_f32_e32 v47, 0, v47
	v_max_f32_e32 v48, 0, v48
	v_max_f32_e32 v49, 0, v49
	v_max_f32_e32 v50, 0, v50
	v_max_f32_e32 v51, 0, v51
	v_max_f32_e32 v52, 0, v52
	v_max_f32_e32 v53, 0, v53
	v_max_f32_e32 v54, 0, v54
	v_max_f32_e32 v55, 0, v55
	v_max_f32_e32 v56, 0, v56
	v_max_f32_e32 v57, 0, v57
	v_max_f32_e32 v58, 0, v58
	v_max_f32_e32 v59, 0, v59
	v_max_f32_e32 v60, 0, v60
	v_max_f32_e32 v61, 0, v61
	v_max_f32_e32 v62, 0, v62
	v_max_f32_e32 v63, 0, v63
	v_max_f32_e32 v64, 0, v64
	v_max_f32_e32 v65, 0, v65
	v_max_f32_e32 v66, 0, v66
	v_max_f32_e32 v67, 0, v67
	v_max_f32_e32 v68, 0, v68
	v_max_f32_e32 v69, 0, v69
	v_max_f32_e32 v70, 0, v70
	v_max_f32_e32 v71, 0, v71
	v_max_f32_e32 v72, 0, v72
	v_max_f32_e32 v73, 0, v73
	v_max_f32_e32 v74, 0, v74
	v_max_f32_e32 v75, 0, v75
	v_max_f32_e32 v76, 0, v76
	v_max_f32_e32 v77, 0, v77
	v_max_f32_e32 v78, 0, v78
	v_max_f32_e32 v79, 0, v79
	v_max_f32_e32 v80, 0, v80
	v_max_f32_e32 v81, 0, v81
	v_max_f32_e32 v82, 0, v82
	v_max_f32_e32 v83, 0, v83
	v_max_f32_e32 v84, 0, v84
	v_max_f32_e32 v85, 0, v85
	v_max_f32_e32 v86, 0, v86
	v_max_f32_e32 v87, 0, v87
	v_max_f32_e32 v88, 0, v88
	v_max_f32_e32 v89, 0, v89
	v_max_f32_e32 v90, 0, v90
	v_max_f32_e32 v91, 0, v91
	v_max_f32_e32 v92, 0, v92
	v_max_f32_e32 v93, 0, v93
	v_max_f32_e32 v94, 0, v94
	v_max_f32_e32 v95, 0, v95
	v_max_f32_e32 v96, 0, v96
	v_max_f32_e32 v97, 0, v97
	v_max_f32_e32 v98, 0, v98
	v_max_f32_e32 v99, 0, v99
	v_max_f32_e32 v100, 0, v100
	v_max_f32_e32 v101, 0, v101
	v_max_f32_e32 v102, 0, v102
	v_max_f32_e32 v103, 0, v103
	v_max_f32_e32 v104, 0, v104
	v_max_f32_e32 v105, 0, v105
	v_max_f32_e32 v106, 0, v106
	v_max_f32_e32 v107, 0, v107
	v_max_f32_e32 v108, 0, v108
	v_max_f32_e32 v109, 0, v109
	v_max_f32_e32 v110, 0, v110
	v_max_f32_e32 v111, 0, v111
	v_max_f32_e32 v116, 0, v116
	v_max_f32_e32 v117, 0, v117
	v_max_f32_e32 v118, 0, v118
	v_max_f32_e32 v119, 0, v119
	v_max_f32_e32 v120, 0, v120
	v_max_f32_e32 v121, 0, v121
	v_max_f32_e32 v122, 0, v122
	v_max_f32_e32 v123, 0, v123
	v_max_f32_e32 v124, 0, v124
	v_max_f32_e32 v125, 0, v125
	v_max_f32_e32 v126, 0, v126
	v_max_f32_e32 v127, 0, v127
	v_max_f32_e32 v128, 0, v128
	v_max_f32_e32 v129, 0, v129
	v_max_f32_e32 v130, 0, v130
	v_max_f32_e32 v131, 0, v131
	v_pk_mul_f32 v[0:1], v[0:1], v[0:1]
	v_pk_mul_f32 v[2:3], v[2:3], v[2:3]
	v_pk_mul_f32 v[4:5], v[4:5], v[4:5]
	v_pk_mul_f32 v[6:7], v[6:7], v[6:7]
	v_pk_mul_f32 v[8:9], v[8:9], v[8:9]
	v_pk_mul_f32 v[10:11], v[10:11], v[10:11]
	v_pk_mul_f32 v[12:13], v[12:13], v[12:13]
	v_pk_mul_f32 v[14:15], v[14:15], v[14:15]
	v_pk_mul_f32 v[16:17], v[16:17], v[16:17]
	v_pk_mul_f32 v[18:19], v[18:19], v[18:19]
	v_pk_mul_f32 v[20:21], v[20:21], v[20:21]
	v_pk_mul_f32 v[22:23], v[22:23], v[22:23]
	v_pk_mul_f32 v[24:25], v[24:25], v[24:25]
	v_pk_mul_f32 v[26:27], v[26:27], v[26:27]
	v_pk_mul_f32 v[28:29], v[28:29], v[28:29]
	v_pk_mul_f32 v[30:31], v[30:31], v[30:31]
	v_pk_mul_f32 v[32:33], v[32:33], v[32:33]
	v_pk_mul_f32 v[34:35], v[34:35], v[34:35]
	v_pk_mul_f32 v[36:37], v[36:37], v[36:37]
	v_pk_mul_f32 v[38:39], v[38:39], v[38:39]
	v_pk_mul_f32 v[40:41], v[40:41], v[40:41]
	v_pk_mul_f32 v[42:43], v[42:43], v[42:43]
	v_pk_mul_f32 v[44:45], v[44:45], v[44:45]
	v_pk_mul_f32 v[46:47], v[46:47], v[46:47]
	v_pk_mul_f32 v[48:49], v[48:49], v[48:49]
	v_pk_mul_f32 v[50:51], v[50:51], v[50:51]
	v_pk_mul_f32 v[52:53], v[52:53], v[52:53]
	v_pk_mul_f32 v[54:55], v[54:55], v[54:55]
	v_pk_mul_f32 v[56:57], v[56:57], v[56:57]
	v_pk_mul_f32 v[58:59], v[58:59], v[58:59]
	v_pk_mul_f32 v[60:61], v[60:61], v[60:61]
	v_pk_mul_f32 v[62:63], v[62:63], v[62:63]
	v_pk_mul_f32 v[64:65], v[64:65], v[64:65]
	v_pk_mul_f32 v[66:67], v[66:67], v[66:67]
	v_pk_mul_f32 v[68:69], v[68:69], v[68:69]
	v_pk_mul_f32 v[70:71], v[70:71], v[70:71]
	v_pk_mul_f32 v[72:73], v[72:73], v[72:73]
	v_pk_mul_f32 v[74:75], v[74:75], v[74:75]
	v_pk_mul_f32 v[76:77], v[76:77], v[76:77]
	v_pk_mul_f32 v[78:79], v[78:79], v[78:79]
	v_pk_mul_f32 v[80:81], v[80:81], v[80:81]
	v_pk_mul_f32 v[82:83], v[82:83], v[82:83]
	v_pk_mul_f32 v[84:85], v[84:85], v[84:85]
	v_pk_mul_f32 v[86:87], v[86:87], v[86:87]
	v_pk_mul_f32 v[88:89], v[88:89], v[88:89]
	v_pk_mul_f32 v[90:91], v[90:91], v[90:91]
	v_pk_mul_f32 v[92:93], v[92:93], v[92:93]
	v_pk_mul_f32 v[94:95], v[94:95], v[94:95]
	v_pk_mul_f32 v[96:97], v[96:97], v[96:97]
	v_pk_mul_f32 v[98:99], v[98:99], v[98:99]
	v_pk_mul_f32 v[100:101], v[100:101], v[100:101]
	v_pk_mul_f32 v[102:103], v[102:103], v[102:103]
	v_pk_mul_f32 v[104:105], v[104:105], v[104:105]
	v_pk_mul_f32 v[106:107], v[106:107], v[106:107]
	v_pk_mul_f32 v[108:109], v[108:109], v[108:109]
	v_pk_mul_f32 v[110:111], v[110:111], v[110:111]
	v_pk_mul_f32 v[116:117], v[116:117], v[116:117]
	v_pk_mul_f32 v[118:119], v[118:119], v[118:119]
	v_pk_mul_f32 v[120:121], v[120:121], v[120:121]
	v_pk_mul_f32 v[122:123], v[122:123], v[122:123]
	v_pk_mul_f32 v[124:125], v[124:125], v[124:125]
	v_pk_mul_f32 v[126:127], v[126:127], v[126:127]
	v_pk_mul_f32 v[128:129], v[128:129], v[128:129]
	v_pk_mul_f32 v[130:131], v[130:131], v[130:131]
.Lg1e_norelu:
	v_cvt_pk_bf16_f32 v128, v128, v129
	v_cvt_pk_bf16_f32 v129, v130, v131
	v_cvt_pk_bf16_f32 v130, v124, v125
	v_cvt_pk_bf16_f32 v131, v126, v127
	v_cvt_pk_bf16_f32 v120, v120, v121
	v_cvt_pk_bf16_f32 v121, v122, v123
	v_cvt_pk_bf16_f32 v122, v116, v117
	v_cvt_pk_bf16_f32 v123, v118, v119
	ds_write_b128 v190, v[128:131]
	ds_write_b128 v190, v[120:123] offset:64
	ds_read_b128 v[192:195], v191
	ds_read_b128 v[196:199], v191 offset:1152
	v_cvt_pk_bf16_f32 v108, v108, v109
	v_cvt_pk_bf16_f32 v109, v110, v111
	v_cvt_pk_bf16_f32 v110, v104, v105
	v_cvt_pk_bf16_f32 v111, v106, v107
	v_cvt_pk_bf16_f32 v100, v100, v101
	v_cvt_pk_bf16_f32 v101, v102, v103
	v_cvt_pk_bf16_f32 v102, v96, v97
	v_cvt_pk_bf16_f32 v103, v98, v99
	s_mul_i32 s20, s6, 32
	v_add_u32_e32 v226, s20, v144
	v_add_u32_e32 v227, s20, v145
	ds_write_b128 v190, v[108:111]
	ds_write_b128 v190, v[100:103] offset:64
	ds_read_b128 v[200:203], v191
	ds_read_b128 v[204:207], v191 offset:1152
	s_waitcnt lgkmcnt(4)
	global_store_dwordx4 v144, v[192:195], s[24:25]
	global_store_dwordx4 v145, v[196:199], s[24:25]
	v_cvt_pk_bf16_f32 v92, v92, v93
	v_cvt_pk_bf16_f32 v93, v94, v95
	v_cvt_pk_bf16_f32 v94, v88, v89
	v_cvt_pk_bf16_f32 v95, v90, v91
	v_cvt_pk_bf16_f32 v84, v84, v85
	v_cvt_pk_bf16_f32 v85, v86, v87
	v_cvt_pk_bf16_f32 v86, v80, v81
	v_cvt_pk_bf16_f32 v87, v82, v83
	s_mul_i32 s20, s6, 64
	v_add_u32_e32 v228, s20, v144
	v_add_u32_e32 v229, s20, v145
	ds_write_b128 v190, v[92:95]
	ds_write_b128 v190, v[84:87] offset:64
	ds_read_b128 v[208:211], v191
	ds_read_b128 v[212:215], v191 offset:1152
	s_waitcnt lgkmcnt(4)
	global_store_dwordx4 v226, v[200:203], s[24:25]
	global_store_dwordx4 v227, v[204:207], s[24:25]
	v_cvt_pk_bf16_f32 v76, v76, v77
	v_cvt_pk_bf16_f32 v77, v78, v79
	v_cvt_pk_bf16_f32 v78, v72, v73
	v_cvt_pk_bf16_f32 v79, v74, v75
	v_cvt_pk_bf16_f32 v68, v68, v69
	v_cvt_pk_bf16_f32 v69, v70, v71
	v_cvt_pk_bf16_f32 v70, v64, v65
	v_cvt_pk_bf16_f32 v71, v66, v67
	s_mul_i32 s20, s6, 96
	v_add_u32_e32 v230, s20, v144
	v_add_u32_e32 v231, s20, v145
	ds_write_b128 v190, v[76:79]
	ds_write_b128 v190, v[68:71] offset:64
	ds_read_b128 v[216:219], v191
	ds_read_b128 v[220:223], v191 offset:1152
	s_waitcnt lgkmcnt(4)
	global_store_dwordx4 v228, v[208:211], s[24:25]
	global_store_dwordx4 v229, v[212:215], s[24:25]
	v_cvt_pk_bf16_f32 v60, v60, v61
	v_cvt_pk_bf16_f32 v61, v62, v63
	v_cvt_pk_bf16_f32 v62, v56, v57
	v_cvt_pk_bf16_f32 v63, v58, v59
	v_cvt_pk_bf16_f32 v52, v52, v53
	v_cvt_pk_bf16_f32 v53, v54, v55
	v_cvt_pk_bf16_f32 v54, v48, v49
	v_cvt_pk_bf16_f32 v55, v50, v51
	s_mul_i32 s20, s6, 256
	v_add_u32_e32 v232, s20, v144
	v_add_u32_e32 v233, s20, v145
	ds_write_b128 v190, v[60:63]
	ds_write_b128 v190, v[52:55] offset:64
	ds_read_b128 v[192:195], v191
	ds_read_b128 v[196:199], v191 offset:1152
	s_waitcnt lgkmcnt(4)
	global_store_dwordx4 v230, v[216:219], s[24:25]
	global_store_dwordx4 v231, v[220:223], s[24:25]
	v_cvt_pk_bf16_f32 v44, v44, v45
	v_cvt_pk_bf16_f32 v45, v46, v47
	v_cvt_pk_bf16_f32 v46, v40, v41
	v_cvt_pk_bf16_f32 v47, v42, v43
	v_cvt_pk_bf16_f32 v36, v36, v37
	v_cvt_pk_bf16_f32 v37, v38, v39
	v_cvt_pk_bf16_f32 v38, v32, v33
	v_cvt_pk_bf16_f32 v39, v34, v35
	s_mul_i32 s20, s6, 288
	v_add_u32_e32 v234, s20, v144
	v_add_u32_e32 v235, s20, v145
	ds_write_b128 v190, v[44:47]
	ds_write_b128 v190, v[36:39] offset:64
	ds_read_b128 v[200:203], v191
	ds_read_b128 v[204:207], v191 offset:1152
	s_waitcnt lgkmcnt(4)
	global_store_dwordx4 v232, v[192:195], s[24:25]
	global_store_dwordx4 v233, v[196:199], s[24:25]
	v_cvt_pk_bf16_f32 v28, v28, v29
	v_cvt_pk_bf16_f32 v29, v30, v31
	v_cvt_pk_bf16_f32 v30, v24, v25
	v_cvt_pk_bf16_f32 v31, v26, v27
	v_cvt_pk_bf16_f32 v20, v20, v21
	v_cvt_pk_bf16_f32 v21, v22, v23
	v_cvt_pk_bf16_f32 v22, v16, v17
	v_cvt_pk_bf16_f32 v23, v18, v19
	s_mul_i32 s20, s6, 320
	v_add_u32_e32 v236, s20, v144
	v_add_u32_e32 v237, s20, v145
	ds_write_b128 v190, v[28:31]
	ds_write_b128 v190, v[20:23] offset:64
	ds_read_b128 v[208:211], v191
	ds_read_b128 v[212:215], v191 offset:1152
	s_waitcnt lgkmcnt(4)
	global_store_dwordx4 v234, v[200:203], s[24:25]
	global_store_dwordx4 v235, v[204:207], s[24:25]
	v_cvt_pk_bf16_f32 v12, v12, v13
	v_cvt_pk_bf16_f32 v13, v14, v15
	v_cvt_pk_bf16_f32 v14, v8, v9
	v_cvt_pk_bf16_f32 v15, v10, v11
	v_cvt_pk_bf16_f32 v4, v4, v5
	v_cvt_pk_bf16_f32 v5, v6, v7
	v_cvt_pk_bf16_f32 v6, v0, v1
	v_cvt_pk_bf16_f32 v7, v2, v3
	s_mul_i32 s20, s6, 352
	v_add_u32_e32 v238, s20, v144
	v_add_u32_e32 v239, s20, v145
	ds_write_b128 v190, v[12:15]
	ds_write_b128 v190, v[4:7] offset:64
	ds_read_b128 v[216:219], v191
	ds_read_b128 v[220:223], v191 offset:1152
	s_waitcnt lgkmcnt(4)
	global_store_dwordx4 v236, v[208:211], s[24:25]
	global_store_dwordx4 v237, v[212:215], s[24:25]
	s_waitcnt lgkmcnt(0)
	global_store_dwordx4 v238, v[216:219], s[24:25]
	global_store_dwordx4 v239, v[220:223], s[24:25]
	s_and_b64 vcc, exec, s[36:37]
	s_mov_b64 s[20:21], -1
	s_cbranch_vccnz .LBB0_662
	s_andn2_b64 vcc, exec, s[14:15]
	s_cbranch_vccnz .LBB0_661
	s_barrier
	s_branch .LBB0_661

	.amdhsa_kernel _Z14fwd_megakernel6Params
		.amdhsa_group_segment_fixed_size 18688
		.amdhsa_private_segment_fixed_size 0
		.amdhsa_kernarg_size 432
		.amdhsa_user_sgpr_count 2
		.amdhsa_user_sgpr_dispatch_ptr 0
		.amdhsa_user_sgpr_queue_ptr 0
		.amdhsa_user_sgpr_kernarg_segment_ptr 1
		.amdhsa_user_sgpr_dispatch_id 0
		.amdhsa_user_sgpr_kernarg_preload_length 0
		.amdhsa_user_sgpr_kernarg_preload_offset 0
		.amdhsa_user_sgpr_private_segment_size 0
		.amdhsa_uses_dynamic_stack 0
		.amdhsa_enable_private_segment 0
		.amdhsa_system_sgpr_workgroup_id_x 1
		.amdhsa_system_sgpr_workgroup_id_y 0
		.amdhsa_system_sgpr_workgroup_id_z 0
		.amdhsa_system_sgpr_workgroup_info 0
		.amdhsa_system_vgpr_workitem_id 2
		.amdhsa_next_free_vgpr 256
		.amdhsa_next_free_sgpr 102
		.amdhsa_accum_offset 256
		.amdhsa_reserve_vcc 1
		.amdhsa_float_round_mode_32 0
		.amdhsa_float_round_mode_16_64 0
		.amdhsa_float_denorm_mode_32 3
		.amdhsa_float_denorm_mode_16_64 3
		.amdhsa_dx10_clamp 1
		.amdhsa_ieee_mode 1
		.amdhsa_fp16_overflow 0
		.amdhsa_tg_split 0
		.amdhsa_exception_fp_ieee_invalid_op 0
		.amdhsa_exception_fp_denorm_src 0
		.amdhsa_exception_fp_ieee_div_zero 0
		.amdhsa_exception_fp_ieee_overflow 0
		.amdhsa_exception_fp_ieee_underflow 0
		.amdhsa_exception_fp_ieee_inexact 0
		.amdhsa_exception_int_div_zero 0
	.end_amdhsa_kernel

amdhsa.kernels:
  - .agpr_count:     0
    .args:
      - .offset:         0
        .size:           176
        .value_kind:     by_value
      - .offset:         176
        .size:           4
        .value_kind:     hidden_block_count_x
      - .offset:         180
        .size:           4
        .value_kind:     hidden_block_count_y
      - .offset:         184
        .size:           4
        .value_kind:     hidden_block_count_z
      - .offset:         188
        .size:           2
        .value_kind:     hidden_group_size_x
      - .offset:         190
        .size:           2
        .value_kind:     hidden_group_size_y
      - .offset:         192
        .size:           2
        .value_kind:     hidden_group_size_z
      - .offset:         194
        .size:           2
        .value_kind:     hidden_remainder_x
      - .offset:         196
        .size:           2
        .value_kind:     hidden_remainder_y
      - .offset:         198
        .size:           2
        .value_kind:     hidden_remainder_z
      - .offset:         216
        .size:           8
        .value_kind:     hidden_global_offset_x
      - .offset:         224
        .size:           8
        .value_kind:     hidden_global_offset_y
      - .offset:         232
        .size:           8
        .value_kind:     hidden_global_offset_z
      - .offset:         240
        .size:           2
        .value_kind:     hidden_grid_dims
      - .offset:         264
        .size:           8
        .value_kind:     hidden_multigrid_sync_arg
      - .offset:         296
        .size:           4
        .value_kind:     hidden_dynamic_lds_size
    .group_segment_fixed_size: 18688
    .kernarg_segment_align: 8
    .kernarg_segment_size: 432
    .language:       OpenCL C
    .language_version:
      - 2
      - 0
    .max_flat_workgroup_size: 512
    .name:           _Z14fwd_megakernel6Params
    .private_segment_fixed_size: 0
    .sgpr_count:     108
    .sgpr_spill_count: 477
    .symbol:         _Z14fwd_megakernel6Params.kd
    .uniform_work_group_size: 1
    .uses_dynamic_stack: false
    .vgpr_count:     256
    .vgpr_spill_count: 0
    .wavefront_size: 64
